# late weight conversion items at the end of the SWA queue are taken by all 256 workgroups (half the items each) instead of only the odd ones; on top of lean P3 epilogue + SGPR-base DMA
# baseline (speedup 1.0000x reference)
; #define LAS __attribute__((address_space(3)))
; #define LDS_BAR() do { asm volatile("s_waitcnt lgkmcnt(0)" ::: "memory"); __builtin_amdgcn_s_barrier(); asm volatile("" ::: "memory"); } while (0)
; __device__ __forceinline__ void p0_weight_item(const Args& a, int idx, LAS float* scr, int lane) {
;     ...
;     r = idx - P0_NEARLY;
;     if (r < P0_I1) { const int kb = r / 176, blk = r % 176; p0_item(a.in[18], 2 * FF, map_ffn_in(blk), 32, a.in[17], 1023, (bf16*)(ws + WS_W2T), D, 0, blk * 32, kb * 64, scr, lane); return; }
;     r -= P0_I1;
;     if (r < P0_I1O) { const int kb = r / 32, blk = r % 32; p0_item(a.in[19], D, blk * 32, 32, nullptr, 0, (bf16*)(ws + WS_W2OT), FF, 0, blk * 32, kb * 64, scr, lane); return; }
;     r -= P0_I1O;
;     if (r < P0_IB) { const int kb = r / 64, blk = r % 64; p0_item(a.in[9], IN_W, map_proj_b(blk), 32, a.in[8], 1023, (bf16*)(ws + WS_WBT), D, 0, blk * 32, kb * 64, scr, lane); return; }
;     r -= P0_IB;
;     if (r < 2 * P0_IBR) { const int which = r / P0_IBR; r -= which * P0_IBR; const int kb = r / 32, blk = r % 32;
;         p0_item(a.in[which ? 15 : 14], D, blk * 32, 32, which ? nullptr : a.in[12], 255, (bf16*)(ws + WS_WBRT), 2 * D, which * D, blk * 32, kb * 64, scr, lane); return; }
;     r -= 2 * P0_IBR;
;     { const int kb = r / 32, blk = r % 32; p0_item(a.in[16], D, blk * 32, 32, nullptr, 0, (bf16*)(ws + WS_WOUTT), D, 0, blk * 32, kb * 64, scr, lane); }
; template <int K> __device__ __forceinline__ void run_phase(const Args& args, LAS unsigned char* ldsp) {
;     ...
;         if (F.vcu & 1) {
;             LDS_BAR();
;             LAS float* scr = (LAS float*)(F.lds + F.wave * 16384);
;             for (int l = (F.vcu >> 1) * NWAVES + F.wave; l < P0_NLATE; l += (F.G >> 1) * NWAVES) p0_weight_item(args, P0_NEARLY + l, scr, F.lane);
;         }
.LBB0_1562:
	s_nop 0
	s_nop 0
	s_lshl_b32 s4, s1, 3
	s_waitcnt lgkmcnt(0)
	s_barrier
	s_and_b32 s4, s4, -8
	s_add_i32 s18, s4, s24
	s_cmpk_gt_i32 s18, 0x1a7f
	s_cbranch_scc1 .LBB0_1761
	v_lshrrev_b32_e32 v69, 3, v7
	s_movk_i32 s5, 0x84
	v_mov_b32_e32 v4, 0xc60
	v_mad_u32_u24 v80, v69, s5, v4
	v_lshlrev_b32_e32 v4, 3, v7
	s_lshl_b32 s4, s24, 14
	v_lshlrev_b32_e32 v2, 2, v7
	v_and_b32_e32 v4, 56, v4
	s_add_i32 s4, s4, 0
	v_and_b32_e32 v2, 28, v2
	v_mul_u32_u24_e32 v5, 0x84, v4
	v_lshlrev_b32_e32 v6, 2, v69
	v_and_b32_e32 v1, 31, v1
	v_lshlrev_b32_e32 v34, 2, v2
	v_add3_u32 v81, s4, v5, v6
	v_lshlrev_b32_e32 v6, 2, v1
	v_add_u32_e32 v77, s4, v34
	v_add_u32_e32 v5, s4, v6
	s_lshl_b32 s4, s0, 3
	s_and_b32 s19, s4, -8
	s_bfe_u32 s4, s3, 0x30006
	s_lshl_b32 s3, s4, 5
	s_add_i32 s6, s3, 0x1490
	s_or_b32 s16, s3, 0x1110
	s_add_u32 s3, s96, 0x1e80000
	s_addc_u32 s20, s97, 0
	v_lshrrev_b32_e32 v82, 5, v7
	v_mov_b32_e32 v7, 0x210
	s_cmp_eq_u64 s[64:65], 0
	v_mad_u32_u24 v9, v82, s5, v7
	v_mov_b32_e32 v7, 0x420
	s_cselect_b64 s[8:9], -1, 0
	s_cmp_lg_u64 s[56:57], 0
	v_mov_b32_e32 v35, 0
	v_mad_u32_u24 v10, v82, s5, v7
	v_mov_b32_e32 v7, 0x630
	s_cselect_b64 s[10:11], -1, 0
	s_cmp_lg_u64 s[82:83], 0
	v_mov_b32_e32 v3, 0x840
	v_mad_u32_u24 v11, v82, s5, v7
	s_cselect_b64 s[12:13], -1, 0
	s_cmp_lg_u64 s[50:51], 0
	v_lshl_add_u64 v[36:37], s[80:81], 0, v[34:35]
	v_lshl_add_u64 v[38:39], s[58:59], 0, v[34:35]
	v_lshl_add_u64 v[40:41], s[86:87], 0, v[34:35]
	v_lshl_add_u64 v[42:43], s[84:85], 0, v[34:35]
	v_mov_b32_e32 v7, v35
	v_lshl_add_u64 v[46:47], s[54:55], 0, v[34:35]
	v_lshl_add_u64 v[48:49], s[52:53], 0, v[34:35]
	v_lshlrev_b32_e32 v34, 1, v4
	v_mad_u32_u24 v79, v69, s5, v3
	v_mad_u32_u24 v3, v82, s5, v3
	s_cselect_b64 s[14:15], -1, 0
	s_cmp_lt_u32 s4, 4
	v_lshl_add_u64 v[44:45], s[58:59], 0, v[6:7]
	v_lshl_add_u64 v[6:7], s[96:97], 0, v[34:35]
	s_mov_b64 s[4:5], 0x2280000
	v_lshl_add_u64 v[50:51], v[6:7], 0, s[4:5]
	s_mov_b64 s[4:5], 0x1a80000
	v_lshl_add_u64 v[52:53], v[6:7], 0, s[4:5]
	s_mov_b64 s[4:5], 0x2f80000
	v_lshl_add_u64 v[54:55], v[6:7], 0, s[4:5]
	s_mov_b64 s[4:5], 0x2480000
	v_lshl_add_u64 v[56:57], v[6:7], 0, s[4:5]
	s_mov_b64 s[4:5], 0x1180000
	v_lshl_add_u64 v[58:59], v[6:7], 0, s[4:5]
	s_mov_b64 s[4:5], 0xc00000
	v_lshl_add_u64 v[60:61], v[6:7], 0, s[4:5]
	s_mov_b64 s[4:5], 0x100000
	s_cselect_b32 s21, s16, s6
	s_lshl_b32 s1, s1, 4
	v_lshl_add_u64 v[62:63], v[6:7], 0, s[4:5]
	s_and_b32 s1, s1, -16
	s_lshl_b32 s4, s24, 1
	v_mul_u32_u24_e32 v8, 0x84, v82
	s_add_i32 s1, s1, s4
	s_mov_b32 s4, s0
	s_add_i32 s5, s18, 0x1980
	s_mov_b32 s7, 0
	v_or_b32_e32 v70, 8, v69
	v_or_b32_e32 v71, 16, v69
	v_or_b32_e32 v72, 24, v69
	v_or_b32_e32 v73, 32, v69
	v_or_b32_e32 v74, 40, v69
	v_or_b32_e32 v75, 48, v69
	v_or_b32_e32 v76, 56, v69
	v_mul_u32_u24_e32 v78, 0x84, v69
	s_lshl_b32 s0, s4, 4
	s_lshl_b32 s22, s5, 5
	s_lshl_b32 s23, s4, 8
	s_lshl_b32 s24, s5, 4
	s_lshl_b32 s25, s4, 7
	v_lshlrev_b32_e32 v64, 2, v2
	v_lshlrev_b32_e32 v66, 1, v4
	s_movk_i32 s26, 0x5800
	v_add_u32_e32 v83, v5, v9
	v_add_u32_e32 v84, v5, v11
	v_mov_b32_e32 v85, 2
	v_add_u32_e32 v86, v5, v8
	v_add_u32_e32 v87, v5, v10
	v_add_u32_e32 v88, v5, v3
	s_branch .LBB0_1567
